# v18 + FFN-in GEMM: per-unit epilogue fold vectors prefetched by LDS-DMA into 2 KB extra LDS during the first k-iteration; epilogue reads them with ds_read_b128 and no longer waits vmcnt(0) on the next
# speedup vs baseline: 1.0078x; 1.0078x over previous
.LBB0_1098:
	s_add_i32 s76, s76, 1
	s_mov_b64 s[62:63], s[54:55]
	s_mul_i32 s54, s76, s26
	s_add_i32 s64, s54, s2
	s_cmpk_gt_i32 s64, 0x57f
	s_cselect_b64 s[60:61], -1, 0
	s_lshl_b32 s54, s64, 3
	s_and_b32 s54, s54, 56
	s_bfe_u32 s55, s64, 0x30003
	s_or_b32 s77, s54, s55
	s_ashr_i32 s58, s64, 6
	s_lshl_b32 s54, s77, 19
	s_mov_b64 s[36:37], s[56:57]
	s_add_u32 s56, s52, s54
	s_addc_u32 s57, s53, 0
	s_ashr_i32 s59, s58, 31
	s_lshl_b64 s[54:55], s[58:59], 19
	s_add_u32 s54, s4, s54
	s_addc_u32 s55, s5, s55
	s_cmpk_lt_i32 s64, 0x580
	s_cselect_b32 s59, s57, s37
	s_cselect_b32 s78, s56, s36
	s_cselect_b32 s79, s55, s63
	s_cselect_b32 s80, s54, s62
	s_add_u32 s81, s62, 0x100
	s_addc_u32 s82, s63, 0
	s_mov_b32 s83, -2
	s_add_u32 s62, s36, 0x100
	s_addc_u32 s63, s37, 0
	s_add_i32 s84, 0, 0x10000
	v_add_u32_e32 v70, s84, v170
	ds_read_b128 v[58:61], v70
	ds_read_b128 v[62:65], v70 offset:1024
	ds_read_b128 v[66:69], v70 offset:2048
	ds_read_b128 v[70:73], v70 offset:3072
	s_cmp_eq_u32 s83, 12
	s_cselect_b32 s67, s59, s63
	s_cselect_b32 s66, s78, s62
	s_cselect_b32 s65, s79, s82
	s_cselect_b32 s64, s80, s81
	v_lshl_add_u64 v[192:193], s[36:37], 0, v[168:169]
	s_add_i32 m0, s69, 0xc000
	ds_read_b128 v[78:81], v175
	ds_read_b128 v[86:89], v175 offset:1024
	ds_read_b128 v[90:93], v175 offset:2048
	ds_read_b128 v[94:97], v175 offset:3072
	ds_read_b128 v[176:179], v175 offset:4096
	ds_read_b128 v[180:183], v175 offset:5120
	ds_read_b128 v[184:187], v175 offset:6144
	ds_read_b128 v[188:191], v175 offset:7168
	global_load_lds_dwordx4 v[192:193], off
	v_lshl_add_u64 v[192:193], s[36:37], 0, v[166:167]
	s_add_i32 m0, s69, 0xe000
	s_nop 0
	global_load_lds_dwordx4 v[192:193], off
	s_waitcnt lgkmcnt(8)
	s_barrier
	s_waitcnt lgkmcnt(0)
	s_setprio 1
	s_waitcnt lgkmcnt(0)
	v_mfma_f32_16x16x32_bf16 v[158:161], v[58:61], v[78:81], 0
	v_mfma_f32_16x16x32_bf16 v[150:153], v[66:69], v[78:81], 0
	v_mfma_f32_16x16x32_bf16 v[142:145], v[58:61], v[90:93], 0
	v_mfma_f32_16x16x32_bf16 v[134:137], v[66:69], v[90:93], 0
	v_mfma_f32_16x16x32_bf16 v[126:129], v[58:61], v[176:179], 0
	v_mfma_f32_16x16x32_bf16 v[118:121], v[66:69], v[176:179], 0
	v_mfma_f32_16x16x32_bf16 v[110:113], v[58:61], v[184:187], 0
	v_mfma_f32_16x16x32_bf16 v[102:105], v[66:69], v[184:187], 0
	v_mfma_f32_16x16x32_bf16 v[158:161], v[62:65], v[86:89], v[158:161]
	v_mfma_f32_16x16x32_bf16 v[150:153], v[70:73], v[86:89], v[150:153]
	v_mfma_f32_16x16x32_bf16 v[142:145], v[62:65], v[94:97], v[142:145]
	v_mfma_f32_16x16x32_bf16 v[134:137], v[70:73], v[94:97], v[134:137]
	v_mfma_f32_16x16x32_bf16 v[126:129], v[62:65], v[180:183], v[126:129]
	v_mfma_f32_16x16x32_bf16 v[118:121], v[70:73], v[180:183], v[118:121]
	v_mfma_f32_16x16x32_bf16 v[110:113], v[62:65], v[188:191], v[110:113]
	v_mfma_f32_16x16x32_bf16 v[102:105], v[70:73], v[188:191], v[102:105]
	s_setprio 0
	s_barrier
	v_mbcnt_lo_u32_b32 v250, -1, 0
	v_mbcnt_hi_u32_b32 v250, -1, v250
	v_lshlrev_b32_e32 v250, 4, v250
	s_lshl_b32 s32, s27, 10
	s_add_u32 s90, s46, s32
	s_addc_u32 s91, s47, 0
	s_add_u32 s92, s48, s32
	s_addc_u32 s93, s49, 0
	s_mov_b32 m0, 0x20840
	s_nop 0
	global_load_lds_dwordx4 v250, s[90:91]
	s_mov_b32 m0, 0x20c40
	s_nop 0
	global_load_lds_dwordx4 v250, s[92:93]
	s_add_i32 s85, 0, 0x14000
	v_add_u32_e32 v192, s85, v170
	s_add_i32 s36, s84, s68
	ds_read_b128 v[200:203], v192
	ds_read_b128 v[204:207], v192 offset:1024
	ds_read_b128 v[208:211], v192 offset:2048
	ds_read_b128 v[222:225], v192 offset:3072
	v_lshl_add_u64 v[192:193], s[64:65], 0, v[164:165]
	s_mov_b32 m0, s36
	v_lshl_add_u64 v[214:215], s[64:65], 0, v[162:163]
	global_load_lds_dwordx4 v[192:193], off
	s_add_i32 m0, s36, 0x2000
	s_nop 0
	global_load_lds_dwordx4 v[214:215], off
	s_barrier
	s_waitcnt lgkmcnt(0)
	s_setprio 1
	s_waitcnt lgkmcnt(0)
	v_mfma_f32_16x16x32_bf16 v[154:157], v[200:203], v[78:81], 0
	v_mfma_f32_16x16x32_bf16 v[78:81], v[208:211], v[78:81], 0
	v_mfma_f32_16x16x32_bf16 v[154:157], v[204:207], v[86:89], v[154:157]
	v_mfma_f32_16x16x32_bf16 v[78:81], v[222:225], v[86:89], v[78:81]
	v_mfma_f32_16x16x32_bf16 v[86:89], v[200:203], v[90:93], 0
	v_mfma_f32_16x16x32_bf16 v[90:93], v[208:211], v[90:93], 0
	v_mfma_f32_16x16x32_bf16 v[114:117], v[208:211], v[176:179], 0
	v_mfma_f32_16x16x32_bf16 v[106:109], v[200:203], v[184:187], 0
	v_mfma_f32_16x16x32_bf16 v[98:101], v[208:211], v[184:187], 0
	v_mfma_f32_16x16x32_bf16 v[86:89], v[204:207], v[94:97], v[86:89]
	v_mfma_f32_16x16x32_bf16 v[90:93], v[222:225], v[94:97], v[90:93]
	v_mfma_f32_16x16x32_bf16 v[94:97], v[200:203], v[176:179], 0
	v_mfma_f32_16x16x32_bf16 v[114:117], v[222:225], v[180:183], v[114:117]
	v_mfma_f32_16x16x32_bf16 v[106:109], v[204:207], v[188:191], v[106:109]
	v_mfma_f32_16x16x32_bf16 v[98:101], v[222:225], v[188:191], v[98:101]
	v_mfma_f32_16x16x32_bf16 v[94:97], v[204:207], v[180:183], v[94:97]
	s_setprio 0
	s_mov_b32 m0, s69
	v_lshl_add_u64 v[234:235], s[66:67], 0, v[164:165]
	s_barrier
	ds_read_b128 v[122:125], v175 offset:16384
	ds_read_b128 v[130:133], v175 offset:17408
	ds_read_b128 v[138:141], v175 offset:18432
	ds_read_b128 v[146:149], v175 offset:19456
	ds_read_b128 v[176:179], v175 offset:20480
	ds_read_b128 v[180:183], v175 offset:21504
	ds_read_b128 v[184:187], v175 offset:22528
	ds_read_b128 v[188:191], v175 offset:23552
	global_load_lds_dwordx4 v[234:235], off
	v_lshl_add_u64 v[236:237], s[66:67], 0, v[162:163]
	s_mov_b32 m0, s70
	s_nop 0
	global_load_lds_dwordx4 v[236:237], off
	s_barrier
	s_waitcnt lgkmcnt(0)
	s_setprio 1
	s_waitcnt lgkmcnt(0)
	v_mfma_f32_16x16x32_bf16 v[82:85], v[58:61], v[122:125], 0
	v_mfma_f32_16x16x32_bf16 v[54:57], v[66:69], v[122:125], 0
	v_mfma_f32_16x16x32_bf16 v[46:49], v[58:61], v[138:141], 0
	v_mfma_f32_16x16x32_bf16 v[38:41], v[66:69], v[138:141], 0
	v_mfma_f32_16x16x32_bf16 v[30:33], v[58:61], v[176:179], 0
	v_mfma_f32_16x16x32_bf16 v[22:25], v[66:69], v[176:179], 0
	v_mfma_f32_16x16x32_bf16 v[14:17], v[58:61], v[184:187], 0
	v_mfma_f32_16x16x32_bf16 v[6:9], v[66:69], v[184:187], 0
	v_mfma_f32_16x16x32_bf16 v[82:85], v[62:65], v[130:133], v[82:85]
	v_mfma_f32_16x16x32_bf16 v[54:57], v[70:73], v[130:133], v[54:57]
	v_mfma_f32_16x16x32_bf16 v[46:49], v[62:65], v[146:149], v[46:49]
	v_mfma_f32_16x16x32_bf16 v[38:41], v[70:73], v[146:149], v[38:41]
	v_mfma_f32_16x16x32_bf16 v[30:33], v[62:65], v[180:183], v[30:33]
	v_mfma_f32_16x16x32_bf16 v[22:25], v[70:73], v[180:183], v[22:25]
	v_mfma_f32_16x16x32_bf16 v[14:17], v[62:65], v[188:191], v[14:17]
	v_mfma_f32_16x16x32_bf16 v[6:9], v[70:73], v[188:191], v[6:9]
	s_setprio 0
	s_barrier
	s_add_u32 s36, s64, 0x40000
	s_addc_u32 s37, s65, 0
	s_add_i32 s84, s85, s68
	v_lshl_add_u64 v[58:59], s[36:37], 0, v[164:165]
	s_mov_b32 m0, s84
	s_nop 0
	global_load_lds_dwordx4 v[58:59], off
	v_lshl_add_u64 v[58:59], s[36:37], 0, v[162:163]
	s_add_i32 m0, s84, 0x2000
	s_nop 0
	global_load_lds_dwordx4 v[58:59], off
	s_waitcnt vmcnt(6)
	s_barrier
	s_setprio 1
	v_mfma_f32_16x16x32_bf16 v[50:53], v[208:211], v[122:125], 0
	v_mfma_f32_16x16x32_bf16 v[42:45], v[200:203], v[138:141], 0
	v_mfma_f32_16x16x32_bf16 v[34:37], v[208:211], v[138:141], 0
	v_mfma_f32_16x16x32_bf16 v[26:29], v[200:203], v[176:179], 0
	v_mfma_f32_16x16x32_bf16 v[18:21], v[208:211], v[176:179], 0
	v_mfma_f32_16x16x32_bf16 v[10:13], v[200:203], v[184:187], 0
	v_mfma_f32_16x16x32_bf16 v[2:5], v[208:211], v[184:187], 0
	v_mfma_f32_16x16x32_bf16 v[58:61], v[200:203], v[122:125], 0
	v_mfma_f32_16x16x32_bf16 v[50:53], v[222:225], v[130:133], v[50:53]
	v_mfma_f32_16x16x32_bf16 v[42:45], v[204:207], v[146:149], v[42:45]
	v_mfma_f32_16x16x32_bf16 v[34:37], v[222:225], v[146:149], v[34:37]
	v_mfma_f32_16x16x32_bf16 v[26:29], v[204:207], v[180:183], v[26:29]
	v_mfma_f32_16x16x32_bf16 v[18:21], v[222:225], v[180:183], v[18:21]
	v_mfma_f32_16x16x32_bf16 v[10:13], v[204:207], v[188:191], v[10:13]
	v_mfma_f32_16x16x32_bf16 v[2:5], v[222:225], v[188:191], v[2:5]
	v_mfma_f32_16x16x32_bf16 v[58:61], v[204:207], v[130:133], v[58:61]
	s_setprio 0
	s_add_i32 s84, 0, 0x18000
	v_add_u32_e32 v74, s84, v170
	s_barrier
	ds_read_b128 v[62:65], v74
	ds_read_b128 v[66:69], v74 offset:1024
	ds_read_b128 v[70:73], v74 offset:2048
	ds_read_b128 v[74:77], v74 offset:3072
	s_add_u32 s36, s66, 0x40000
	s_addc_u32 s37, s67, 0
	s_mov_b32 m0, s71
	v_lshl_add_u64 v[138:139], s[36:37], 0, v[164:165]
	ds_read_b128 v[122:125], v175 offset:32768
	ds_read_b128 v[130:133], v175 offset:33792
	ds_read_b128 v[176:179], v175 offset:34816
	ds_read_b128 v[180:183], v175 offset:35840
	ds_read_b128 v[184:187], v175 offset:36864
	ds_read_b128 v[188:191], v175 offset:37888
	ds_read_b128 v[200:203], v175 offset:38912
	ds_read_b128 v[204:207], v175 offset:39936
	global_load_lds_dwordx4 v[138:139], off
	v_lshl_add_u64 v[138:139], s[36:37], 0, v[162:163]
	s_mov_b32 m0, s72
	s_nop 0
	global_load_lds_dwordx4 v[138:139], off
	s_waitcnt lgkmcnt(8)
	s_barrier
	s_waitcnt lgkmcnt(0)
	s_setprio 1
	s_waitcnt lgkmcnt(0)
	v_mfma_f32_16x16x32_bf16 v[138:141], v[62:65], v[122:125], v[158:161]
	v_mfma_f32_16x16x32_bf16 v[158:161], v[66:69], v[130:133], v[138:141]
	v_mfma_f32_16x16x32_bf16 v[138:141], v[70:73], v[122:125], v[150:153]
	v_mfma_f32_16x16x32_bf16 v[150:153], v[74:77], v[130:133], v[138:141]
	v_mfma_f32_16x16x32_bf16 v[138:141], v[62:65], v[176:179], v[142:145]
	v_mfma_f32_16x16x32_bf16 v[134:137], v[70:73], v[176:179], v[134:137]
	v_mfma_f32_16x16x32_bf16 v[126:129], v[62:65], v[184:187], v[126:129]
	v_mfma_f32_16x16x32_bf16 v[118:121], v[70:73], v[184:187], v[118:121]
	v_mfma_f32_16x16x32_bf16 v[110:113], v[62:65], v[200:203], v[110:113]
	v_mfma_f32_16x16x32_bf16 v[102:105], v[70:73], v[200:203], v[102:105]
	v_mfma_f32_16x16x32_bf16 v[142:145], v[66:69], v[180:183], v[138:141]
	v_mfma_f32_16x16x32_bf16 v[134:137], v[74:77], v[180:183], v[134:137]
	v_mfma_f32_16x16x32_bf16 v[126:129], v[66:69], v[188:191], v[126:129]
	v_mfma_f32_16x16x32_bf16 v[118:121], v[74:77], v[188:191], v[118:121]
	v_mfma_f32_16x16x32_bf16 v[110:113], v[66:69], v[204:207], v[110:113]
	v_mfma_f32_16x16x32_bf16 v[102:105], v[74:77], v[204:207], v[102:105]
	s_setprio 0
	s_barrier
	s_add_i32 s66, 0, 0x1c000
	v_add_u32_e32 v138, s66, v170
	s_add_i32 s36, s84, s68
	ds_read_b128 v[208:211], v138
	ds_read_b128 v[222:225], v138 offset:1024
	ds_read_b128 v[226:229], v138 offset:2048
	ds_read_b128 v[230:233], v138 offset:3072
	v_lshl_add_u64 v[138:139], v[192:193], 0, s[22:23]
	s_mov_b32 m0, s36
	s_nop 0
	global_load_lds_dwordx4 v[138:139], off
	v_lshl_add_u64 v[138:139], v[214:215], 0, s[22:23]
	s_add_i32 m0, s36, 0x2000
	s_nop 0
	global_load_lds_dwordx4 v[138:139], off
	s_barrier
	s_waitcnt lgkmcnt(0)
	s_setprio 1
	s_waitcnt lgkmcnt(0)
	v_mfma_f32_16x16x32_bf16 v[78:81], v[226:229], v[122:125], v[78:81]
	v_mfma_f32_16x16x32_bf16 v[138:141], v[208:211], v[122:125], v[154:157]
	v_mfma_f32_16x16x32_bf16 v[146:149], v[230:233], v[130:133], v[78:81]
	v_mfma_f32_16x16x32_bf16 v[78:81], v[208:211], v[176:179], v[86:89]
	v_mfma_f32_16x16x32_bf16 v[154:157], v[222:225], v[130:133], v[138:141]
	v_mfma_f32_16x16x32_bf16 v[138:141], v[222:225], v[180:183], v[78:81]
	v_mfma_f32_16x16x32_bf16 v[78:81], v[226:229], v[176:179], v[90:93]
	v_mfma_f32_16x16x32_bf16 v[130:133], v[230:233], v[180:183], v[78:81]
	v_mfma_f32_16x16x32_bf16 v[78:81], v[208:211], v[184:187], v[94:97]
	v_mfma_f32_16x16x32_bf16 v[122:125], v[222:225], v[188:191], v[78:81]
	v_mfma_f32_16x16x32_bf16 v[78:81], v[226:229], v[184:187], v[114:117]
	v_mfma_f32_16x16x32_bf16 v[114:117], v[230:233], v[188:191], v[78:81]
	v_mfma_f32_16x16x32_bf16 v[78:81], v[208:211], v[200:203], v[106:109]
	v_mfma_f32_16x16x32_bf16 v[106:109], v[222:225], v[204:207], v[78:81]
	v_mfma_f32_16x16x32_bf16 v[78:81], v[226:229], v[200:203], v[98:101]
	v_mfma_f32_16x16x32_bf16 v[98:101], v[230:233], v[204:207], v[78:81]
	s_setprio 0
	s_mov_b32 m0, s73
	v_lshl_add_u64 v[192:193], v[234:235], 0, s[22:23]
	s_barrier
	s_nop 2
	ds_read_b128 v[78:81], v175 offset:49152
	ds_read_b128 v[86:89], v175 offset:50176
	ds_read_b128 v[90:93], v175 offset:51200
	ds_read_b128 v[94:97], v175 offset:52224
	ds_read_b128 v[176:179], v175 offset:53248
	ds_read_b128 v[180:183], v175 offset:54272
	ds_read_b128 v[184:187], v175 offset:55296
	ds_read_b128 v[188:191], v175 offset:56320
	global_load_lds_dwordx4 v[192:193], off
	v_lshl_add_u64 v[192:193], v[236:237], 0, s[22:23]
	s_mov_b32 m0, s75
	s_nop 0
	global_load_lds_dwordx4 v[192:193], off
	s_barrier
	s_waitcnt lgkmcnt(0)
	s_setprio 1
	s_waitcnt lgkmcnt(0)
	v_mfma_f32_16x16x32_bf16 v[82:85], v[62:65], v[78:81], v[82:85]
	v_mfma_f32_16x16x32_bf16 v[54:57], v[70:73], v[78:81], v[54:57]
	v_mfma_f32_16x16x32_bf16 v[46:49], v[62:65], v[90:93], v[46:49]
	v_mfma_f32_16x16x32_bf16 v[38:41], v[70:73], v[90:93], v[38:41]
	v_mfma_f32_16x16x32_bf16 v[30:33], v[62:65], v[176:179], v[30:33]
	v_mfma_f32_16x16x32_bf16 v[22:25], v[70:73], v[176:179], v[22:25]
	v_mfma_f32_16x16x32_bf16 v[14:17], v[62:65], v[184:187], v[14:17]
	v_mfma_f32_16x16x32_bf16 v[6:9], v[70:73], v[184:187], v[6:9]
	v_mfma_f32_16x16x32_bf16 v[82:85], v[66:69], v[86:89], v[82:85]
	v_mfma_f32_16x16x32_bf16 v[54:57], v[74:77], v[86:89], v[54:57]
	v_mfma_f32_16x16x32_bf16 v[46:49], v[66:69], v[94:97], v[46:49]
	v_mfma_f32_16x16x32_bf16 v[38:41], v[74:77], v[94:97], v[38:41]
	v_mfma_f32_16x16x32_bf16 v[30:33], v[66:69], v[180:183], v[30:33]
	v_mfma_f32_16x16x32_bf16 v[22:25], v[74:77], v[180:183], v[22:25]
	v_mfma_f32_16x16x32_bf16 v[14:17], v[66:69], v[188:191], v[14:17]
	v_mfma_f32_16x16x32_bf16 v[6:9], v[74:77], v[188:191], v[6:9]
	s_setprio 0
	s_barrier
	s_add_u32 s36, s64, 0x40080
	s_addc_u32 s37, s65, 0
	s_add_i32 s64, s66, s68
	v_lshl_add_u64 v[62:63], s[36:37], 0, v[164:165]
	s_mov_b32 m0, s64
	s_nop 0
	global_load_lds_dwordx4 v[62:63], off
	v_lshl_add_u64 v[62:63], s[36:37], 0, v[162:163]
	s_add_i32 m0, s64, 0x2000
	s_nop 0
	global_load_lds_dwordx4 v[62:63], off
	s_waitcnt vmcnt(6)
	s_barrier
	s_setprio 1
	v_mfma_f32_16x16x32_bf16 v[58:61], v[208:211], v[78:81], v[58:61]
	v_mfma_f32_16x16x32_bf16 v[50:53], v[226:229], v[78:81], v[50:53]
	v_mfma_f32_16x16x32_bf16 v[42:45], v[208:211], v[90:93], v[42:45]
	v_mfma_f32_16x16x32_bf16 v[34:37], v[226:229], v[90:93], v[34:37]
	v_mfma_f32_16x16x32_bf16 v[26:29], v[208:211], v[176:179], v[26:29]
	v_mfma_f32_16x16x32_bf16 v[18:21], v[226:229], v[176:179], v[18:21]
	v_mfma_f32_16x16x32_bf16 v[10:13], v[208:211], v[184:187], v[10:13]
	v_mfma_f32_16x16x32_bf16 v[2:5], v[226:229], v[184:187], v[2:5]
	v_mfma_f32_16x16x32_bf16 v[74:77], v[222:225], v[86:89], v[58:61]
	v_mfma_f32_16x16x32_bf16 v[50:53], v[230:233], v[86:89], v[50:53]
	v_mfma_f32_16x16x32_bf16 v[42:45], v[222:225], v[94:97], v[42:45]
	v_mfma_f32_16x16x32_bf16 v[34:37], v[230:233], v[94:97], v[34:37]
	v_mfma_f32_16x16x32_bf16 v[26:29], v[222:225], v[180:183], v[26:29]
	v_mfma_f32_16x16x32_bf16 v[18:21], v[230:233], v[180:183], v[18:21]
	v_mfma_f32_16x16x32_bf16 v[10:13], v[222:225], v[188:191], v[10:13]
	v_mfma_f32_16x16x32_bf16 v[2:5], v[230:233], v[188:191], v[2:5]
	s_setprio 0
	s_add_i32 s83, s83, 2
	s_add_u32 s81, s81, 0x100
	s_addc_u32 s82, s82, 0
	s_cmp_gt_u32 s83, 13
	s_mov_b64 s[36:37], s[62:63]
	s_barrier
.LBB0_1099:
	s_add_u32 s62, s36, 0x100
	s_addc_u32 s63, s37, 0
	s_add_i32 s84, 0, 0x10000
	v_add_u32_e32 v70, s84, v170
	ds_read_b128 v[58:61], v70
	ds_read_b128 v[62:65], v70 offset:1024
	ds_read_b128 v[66:69], v70 offset:2048
	ds_read_b128 v[70:73], v70 offset:3072
	s_cmp_eq_u32 s83, 12
	s_cselect_b32 s67, s59, s63
	s_cselect_b32 s66, s78, s62
	s_cselect_b32 s65, s79, s82
	s_cselect_b32 s64, s80, s81
	v_lshl_add_u64 v[192:193], s[36:37], 0, v[168:169]
	s_add_i32 m0, s69, 0xc000
	ds_read_b128 v[78:81], v175
	ds_read_b128 v[86:89], v175 offset:1024
	ds_read_b128 v[90:93], v175 offset:2048
	ds_read_b128 v[94:97], v175 offset:3072
	ds_read_b128 v[176:179], v175 offset:4096
	ds_read_b128 v[180:183], v175 offset:5120
	ds_read_b128 v[184:187], v175 offset:6144
	ds_read_b128 v[188:191], v175 offset:7168
	global_load_lds_dwordx4 v[192:193], off
	v_lshl_add_u64 v[192:193], s[36:37], 0, v[166:167]
	s_add_i32 m0, s69, 0xe000
	s_nop 0
	global_load_lds_dwordx4 v[192:193], off
	s_waitcnt lgkmcnt(8)
	s_barrier
	s_waitcnt lgkmcnt(0)
	s_setprio 1
	s_waitcnt lgkmcnt(0)
	v_mfma_f32_16x16x32_bf16 v[158:161], v[58:61], v[78:81], v[158:161]
	v_mfma_f32_16x16x32_bf16 v[150:153], v[66:69], v[78:81], v[150:153]
	v_mfma_f32_16x16x32_bf16 v[142:145], v[58:61], v[90:93], v[142:145]
	v_mfma_f32_16x16x32_bf16 v[134:137], v[66:69], v[90:93], v[134:137]
	v_mfma_f32_16x16x32_bf16 v[126:129], v[58:61], v[176:179], v[126:129]
	v_mfma_f32_16x16x32_bf16 v[118:121], v[66:69], v[176:179], v[118:121]
	v_mfma_f32_16x16x32_bf16 v[110:113], v[58:61], v[184:187], v[110:113]
	v_mfma_f32_16x16x32_bf16 v[102:105], v[66:69], v[184:187], v[102:105]
	v_mfma_f32_16x16x32_bf16 v[158:161], v[62:65], v[86:89], v[158:161]
	v_mfma_f32_16x16x32_bf16 v[150:153], v[70:73], v[86:89], v[150:153]
	v_mfma_f32_16x16x32_bf16 v[142:145], v[62:65], v[94:97], v[142:145]
	v_mfma_f32_16x16x32_bf16 v[134:137], v[70:73], v[94:97], v[134:137]
	v_mfma_f32_16x16x32_bf16 v[126:129], v[62:65], v[180:183], v[126:129]
	v_mfma_f32_16x16x32_bf16 v[118:121], v[70:73], v[180:183], v[118:121]
	v_mfma_f32_16x16x32_bf16 v[110:113], v[62:65], v[188:191], v[110:113]
	v_mfma_f32_16x16x32_bf16 v[102:105], v[70:73], v[188:191], v[102:105]
	s_setprio 0
	s_barrier
	s_add_i32 s85, 0, 0x14000
	v_add_u32_e32 v192, s85, v170
	s_add_i32 s36, s84, s68
	ds_read_b128 v[200:203], v192
	ds_read_b128 v[204:207], v192 offset:1024
	ds_read_b128 v[208:211], v192 offset:2048
	ds_read_b128 v[222:225], v192 offset:3072
	v_lshl_add_u64 v[192:193], s[64:65], 0, v[164:165]
	s_mov_b32 m0, s36
	v_lshl_add_u64 v[214:215], s[64:65], 0, v[162:163]
	global_load_lds_dwordx4 v[192:193], off
	s_add_i32 m0, s36, 0x2000
	s_nop 0
	global_load_lds_dwordx4 v[214:215], off
	s_barrier
	s_waitcnt lgkmcnt(0)
	s_setprio 1
	s_waitcnt lgkmcnt(0)
	v_mfma_f32_16x16x32_bf16 v[154:157], v[200:203], v[78:81], v[154:157]
	v_mfma_f32_16x16x32_bf16 v[78:81], v[208:211], v[78:81], v[146:149]
	v_mfma_f32_16x16x32_bf16 v[154:157], v[204:207], v[86:89], v[154:157]
	v_mfma_f32_16x16x32_bf16 v[78:81], v[222:225], v[86:89], v[78:81]
	v_mfma_f32_16x16x32_bf16 v[86:89], v[200:203], v[90:93], v[138:141]
	v_mfma_f32_16x16x32_bf16 v[90:93], v[208:211], v[90:93], v[130:133]
	v_mfma_f32_16x16x32_bf16 v[114:117], v[208:211], v[176:179], v[114:117]
	v_mfma_f32_16x16x32_bf16 v[106:109], v[200:203], v[184:187], v[106:109]
	v_mfma_f32_16x16x32_bf16 v[98:101], v[208:211], v[184:187], v[98:101]
	v_mfma_f32_16x16x32_bf16 v[86:89], v[204:207], v[94:97], v[86:89]
	v_mfma_f32_16x16x32_bf16 v[90:93], v[222:225], v[94:97], v[90:93]
	v_mfma_f32_16x16x32_bf16 v[94:97], v[200:203], v[176:179], v[122:125]
	v_mfma_f32_16x16x32_bf16 v[114:117], v[222:225], v[180:183], v[114:117]
	v_mfma_f32_16x16x32_bf16 v[106:109], v[204:207], v[188:191], v[106:109]
	v_mfma_f32_16x16x32_bf16 v[98:101], v[222:225], v[188:191], v[98:101]
	v_mfma_f32_16x16x32_bf16 v[94:97], v[204:207], v[180:183], v[94:97]
	s_setprio 0
	s_mov_b32 m0, s69
	v_lshl_add_u64 v[234:235], s[66:67], 0, v[164:165]
	s_barrier
	ds_read_b128 v[122:125], v175 offset:16384
	ds_read_b128 v[130:133], v175 offset:17408
	ds_read_b128 v[138:141], v175 offset:18432
	ds_read_b128 v[146:149], v175 offset:19456
	ds_read_b128 v[176:179], v175 offset:20480
	ds_read_b128 v[180:183], v175 offset:21504
	ds_read_b128 v[184:187], v175 offset:22528
	ds_read_b128 v[188:191], v175 offset:23552
	global_load_lds_dwordx4 v[234:235], off
	v_lshl_add_u64 v[236:237], s[66:67], 0, v[162:163]
	s_mov_b32 m0, s70
	s_nop 0
	global_load_lds_dwordx4 v[236:237], off
	s_barrier
	s_waitcnt lgkmcnt(0)
	s_setprio 1
	s_waitcnt lgkmcnt(0)
	v_mfma_f32_16x16x32_bf16 v[82:85], v[58:61], v[122:125], v[82:85]
	v_mfma_f32_16x16x32_bf16 v[54:57], v[66:69], v[122:125], v[54:57]
	v_mfma_f32_16x16x32_bf16 v[46:49], v[58:61], v[138:141], v[46:49]
	v_mfma_f32_16x16x32_bf16 v[38:41], v[66:69], v[138:141], v[38:41]
	v_mfma_f32_16x16x32_bf16 v[30:33], v[58:61], v[176:179], v[30:33]
	v_mfma_f32_16x16x32_bf16 v[22:25], v[66:69], v[176:179], v[22:25]
	v_mfma_f32_16x16x32_bf16 v[14:17], v[58:61], v[184:187], v[14:17]
	v_mfma_f32_16x16x32_bf16 v[6:9], v[66:69], v[184:187], v[6:9]
	v_mfma_f32_16x16x32_bf16 v[82:85], v[62:65], v[130:133], v[82:85]
	v_mfma_f32_16x16x32_bf16 v[54:57], v[70:73], v[130:133], v[54:57]
	v_mfma_f32_16x16x32_bf16 v[46:49], v[62:65], v[146:149], v[46:49]
	v_mfma_f32_16x16x32_bf16 v[38:41], v[70:73], v[146:149], v[38:41]
	v_mfma_f32_16x16x32_bf16 v[30:33], v[62:65], v[180:183], v[30:33]
	v_mfma_f32_16x16x32_bf16 v[22:25], v[70:73], v[180:183], v[22:25]
	v_mfma_f32_16x16x32_bf16 v[14:17], v[62:65], v[188:191], v[14:17]
	v_mfma_f32_16x16x32_bf16 v[6:9], v[70:73], v[188:191], v[6:9]
	s_setprio 0
	s_barrier
	s_add_u32 s36, s64, 0x40000
	s_addc_u32 s37, s65, 0
	s_add_i32 s84, s85, s68
	v_lshl_add_u64 v[58:59], s[36:37], 0, v[164:165]
	s_mov_b32 m0, s84
	s_nop 0
	global_load_lds_dwordx4 v[58:59], off
	v_lshl_add_u64 v[58:59], s[36:37], 0, v[162:163]
	s_add_i32 m0, s84, 0x2000
	s_nop 0
	global_load_lds_dwordx4 v[58:59], off
	s_waitcnt vmcnt(6)
	s_barrier
	s_setprio 1
	v_mfma_f32_16x16x32_bf16 v[50:53], v[208:211], v[122:125], v[50:53]
	v_mfma_f32_16x16x32_bf16 v[42:45], v[200:203], v[138:141], v[42:45]
	v_mfma_f32_16x16x32_bf16 v[34:37], v[208:211], v[138:141], v[34:37]
	v_mfma_f32_16x16x32_bf16 v[26:29], v[200:203], v[176:179], v[26:29]
	v_mfma_f32_16x16x32_bf16 v[18:21], v[208:211], v[176:179], v[18:21]
	v_mfma_f32_16x16x32_bf16 v[10:13], v[200:203], v[184:187], v[10:13]
	v_mfma_f32_16x16x32_bf16 v[2:5], v[208:211], v[184:187], v[2:5]
	v_mfma_f32_16x16x32_bf16 v[58:61], v[200:203], v[122:125], v[74:77]
	v_mfma_f32_16x16x32_bf16 v[50:53], v[222:225], v[130:133], v[50:53]
	v_mfma_f32_16x16x32_bf16 v[42:45], v[204:207], v[146:149], v[42:45]
	v_mfma_f32_16x16x32_bf16 v[34:37], v[222:225], v[146:149], v[34:37]
	v_mfma_f32_16x16x32_bf16 v[26:29], v[204:207], v[180:183], v[26:29]
	v_mfma_f32_16x16x32_bf16 v[18:21], v[222:225], v[180:183], v[18:21]
	v_mfma_f32_16x16x32_bf16 v[10:13], v[204:207], v[188:191], v[10:13]
	v_mfma_f32_16x16x32_bf16 v[2:5], v[222:225], v[188:191], v[2:5]
	v_mfma_f32_16x16x32_bf16 v[58:61], v[204:207], v[130:133], v[58:61]
	s_setprio 0
	s_add_i32 s84, 0, 0x18000
	v_add_u32_e32 v74, s84, v170
	s_barrier
	ds_read_b128 v[62:65], v74
	ds_read_b128 v[66:69], v74 offset:1024
	ds_read_b128 v[70:73], v74 offset:2048
	ds_read_b128 v[74:77], v74 offset:3072
	s_add_u32 s36, s66, 0x40000
	s_addc_u32 s37, s67, 0
	s_mov_b32 m0, s71
	v_lshl_add_u64 v[138:139], s[36:37], 0, v[164:165]
	ds_read_b128 v[122:125], v175 offset:32768
	ds_read_b128 v[130:133], v175 offset:33792
	ds_read_b128 v[176:179], v175 offset:34816
	ds_read_b128 v[180:183], v175 offset:35840
	ds_read_b128 v[184:187], v175 offset:36864
	ds_read_b128 v[188:191], v175 offset:37888
	ds_read_b128 v[200:203], v175 offset:38912
	ds_read_b128 v[204:207], v175 offset:39936
	global_load_lds_dwordx4 v[138:139], off
	v_lshl_add_u64 v[138:139], s[36:37], 0, v[162:163]
	s_mov_b32 m0, s72
	s_nop 0
	global_load_lds_dwordx4 v[138:139], off
	s_waitcnt lgkmcnt(8)
	s_barrier
	s_waitcnt lgkmcnt(0)
	s_setprio 1
	s_waitcnt lgkmcnt(0)
	v_mfma_f32_16x16x32_bf16 v[138:141], v[62:65], v[122:125], v[158:161]
	v_mfma_f32_16x16x32_bf16 v[158:161], v[66:69], v[130:133], v[138:141]
	v_mfma_f32_16x16x32_bf16 v[138:141], v[70:73], v[122:125], v[150:153]
	v_mfma_f32_16x16x32_bf16 v[150:153], v[74:77], v[130:133], v[138:141]
	v_mfma_f32_16x16x32_bf16 v[138:141], v[62:65], v[176:179], v[142:145]
	v_mfma_f32_16x16x32_bf16 v[134:137], v[70:73], v[176:179], v[134:137]
	v_mfma_f32_16x16x32_bf16 v[126:129], v[62:65], v[184:187], v[126:129]
	v_mfma_f32_16x16x32_bf16 v[118:121], v[70:73], v[184:187], v[118:121]
	v_mfma_f32_16x16x32_bf16 v[110:113], v[62:65], v[200:203], v[110:113]
	v_mfma_f32_16x16x32_bf16 v[102:105], v[70:73], v[200:203], v[102:105]
	v_mfma_f32_16x16x32_bf16 v[142:145], v[66:69], v[180:183], v[138:141]
	v_mfma_f32_16x16x32_bf16 v[134:137], v[74:77], v[180:183], v[134:137]
	v_mfma_f32_16x16x32_bf16 v[126:129], v[66:69], v[188:191], v[126:129]
	v_mfma_f32_16x16x32_bf16 v[118:121], v[74:77], v[188:191], v[118:121]
	v_mfma_f32_16x16x32_bf16 v[110:113], v[66:69], v[204:207], v[110:113]
	v_mfma_f32_16x16x32_bf16 v[102:105], v[74:77], v[204:207], v[102:105]
	s_setprio 0
	s_barrier
	s_add_i32 s66, 0, 0x1c000
	v_add_u32_e32 v138, s66, v170
	s_add_i32 s36, s84, s68
	ds_read_b128 v[208:211], v138
	ds_read_b128 v[222:225], v138 offset:1024
	ds_read_b128 v[226:229], v138 offset:2048
	ds_read_b128 v[230:233], v138 offset:3072
	v_lshl_add_u64 v[138:139], v[192:193], 0, s[22:23]
	s_mov_b32 m0, s36
	s_nop 0
	global_load_lds_dwordx4 v[138:139], off
	v_lshl_add_u64 v[138:139], v[214:215], 0, s[22:23]
	s_add_i32 m0, s36, 0x2000
	s_nop 0
	global_load_lds_dwordx4 v[138:139], off
	s_barrier
	s_waitcnt lgkmcnt(0)
	s_setprio 1
	s_waitcnt lgkmcnt(0)
	v_mfma_f32_16x16x32_bf16 v[78:81], v[226:229], v[122:125], v[78:81]
	v_mfma_f32_16x16x32_bf16 v[138:141], v[208:211], v[122:125], v[154:157]
	v_mfma_f32_16x16x32_bf16 v[146:149], v[230:233], v[130:133], v[78:81]
	v_mfma_f32_16x16x32_bf16 v[78:81], v[208:211], v[176:179], v[86:89]
	v_mfma_f32_16x16x32_bf16 v[154:157], v[222:225], v[130:133], v[138:141]
	v_mfma_f32_16x16x32_bf16 v[138:141], v[222:225], v[180:183], v[78:81]
	v_mfma_f32_16x16x32_bf16 v[78:81], v[226:229], v[176:179], v[90:93]
	v_mfma_f32_16x16x32_bf16 v[130:133], v[230:233], v[180:183], v[78:81]
	v_mfma_f32_16x16x32_bf16 v[78:81], v[208:211], v[184:187], v[94:97]
	v_mfma_f32_16x16x32_bf16 v[122:125], v[222:225], v[188:191], v[78:81]
	v_mfma_f32_16x16x32_bf16 v[78:81], v[226:229], v[184:187], v[114:117]
	v_mfma_f32_16x16x32_bf16 v[114:117], v[230:233], v[188:191], v[78:81]
	v_mfma_f32_16x16x32_bf16 v[78:81], v[208:211], v[200:203], v[106:109]
	v_mfma_f32_16x16x32_bf16 v[106:109], v[222:225], v[204:207], v[78:81]
	v_mfma_f32_16x16x32_bf16 v[78:81], v[226:229], v[200:203], v[98:101]
	v_mfma_f32_16x16x32_bf16 v[98:101], v[230:233], v[204:207], v[78:81]
	s_setprio 0
	s_mov_b32 m0, s73
	v_lshl_add_u64 v[192:193], v[234:235], 0, s[22:23]
	s_barrier
	s_nop 2
	ds_read_b128 v[78:81], v175 offset:49152
	ds_read_b128 v[86:89], v175 offset:50176
	ds_read_b128 v[90:93], v175 offset:51200
	ds_read_b128 v[94:97], v175 offset:52224
	ds_read_b128 v[176:179], v175 offset:53248
	ds_read_b128 v[180:183], v175 offset:54272
	ds_read_b128 v[184:187], v175 offset:55296
	ds_read_b128 v[188:191], v175 offset:56320
	global_load_lds_dwordx4 v[192:193], off
	v_lshl_add_u64 v[192:193], v[236:237], 0, s[22:23]
	s_mov_b32 m0, s75
	s_nop 0
	global_load_lds_dwordx4 v[192:193], off
	s_barrier
	s_waitcnt lgkmcnt(0)
	s_setprio 1
	s_waitcnt lgkmcnt(0)
	v_mfma_f32_16x16x32_bf16 v[82:85], v[62:65], v[78:81], v[82:85]
	v_mfma_f32_16x16x32_bf16 v[54:57], v[70:73], v[78:81], v[54:57]
	v_mfma_f32_16x16x32_bf16 v[46:49], v[62:65], v[90:93], v[46:49]
	v_mfma_f32_16x16x32_bf16 v[38:41], v[70:73], v[90:93], v[38:41]
	v_mfma_f32_16x16x32_bf16 v[30:33], v[62:65], v[176:179], v[30:33]
	v_mfma_f32_16x16x32_bf16 v[22:25], v[70:73], v[176:179], v[22:25]
	v_mfma_f32_16x16x32_bf16 v[14:17], v[62:65], v[184:187], v[14:17]
	v_mfma_f32_16x16x32_bf16 v[6:9], v[70:73], v[184:187], v[6:9]
	v_mfma_f32_16x16x32_bf16 v[82:85], v[66:69], v[86:89], v[82:85]
	v_mfma_f32_16x16x32_bf16 v[54:57], v[74:77], v[86:89], v[54:57]
	v_mfma_f32_16x16x32_bf16 v[46:49], v[66:69], v[94:97], v[46:49]
	v_mfma_f32_16x16x32_bf16 v[38:41], v[74:77], v[94:97], v[38:41]
	v_mfma_f32_16x16x32_bf16 v[30:33], v[66:69], v[180:183], v[30:33]
	v_mfma_f32_16x16x32_bf16 v[22:25], v[74:77], v[180:183], v[22:25]
	v_mfma_f32_16x16x32_bf16 v[14:17], v[66:69], v[188:191], v[14:17]
	v_mfma_f32_16x16x32_bf16 v[6:9], v[74:77], v[188:191], v[6:9]
	s_setprio 0
	s_barrier
	s_add_u32 s36, s64, 0x40080
	s_addc_u32 s37, s65, 0
	s_add_i32 s64, s66, s68
	v_lshl_add_u64 v[62:63], s[36:37], 0, v[164:165]
	s_mov_b32 m0, s64
	s_nop 0
	global_load_lds_dwordx4 v[62:63], off
	v_lshl_add_u64 v[62:63], s[36:37], 0, v[162:163]
	s_add_i32 m0, s64, 0x2000
	s_nop 0
	global_load_lds_dwordx4 v[62:63], off
	s_waitcnt vmcnt(6)
	s_barrier
	s_setprio 1
	v_mfma_f32_16x16x32_bf16 v[58:61], v[208:211], v[78:81], v[58:61]
	v_mfma_f32_16x16x32_bf16 v[50:53], v[226:229], v[78:81], v[50:53]
	v_mfma_f32_16x16x32_bf16 v[42:45], v[208:211], v[90:93], v[42:45]
	v_mfma_f32_16x16x32_bf16 v[34:37], v[226:229], v[90:93], v[34:37]
	v_mfma_f32_16x16x32_bf16 v[26:29], v[208:211], v[176:179], v[26:29]
	v_mfma_f32_16x16x32_bf16 v[18:21], v[226:229], v[176:179], v[18:21]
	v_mfma_f32_16x16x32_bf16 v[10:13], v[208:211], v[184:187], v[10:13]
	v_mfma_f32_16x16x32_bf16 v[2:5], v[226:229], v[184:187], v[2:5]
	v_mfma_f32_16x16x32_bf16 v[74:77], v[222:225], v[86:89], v[58:61]
	v_mfma_f32_16x16x32_bf16 v[50:53], v[230:233], v[86:89], v[50:53]
	v_mfma_f32_16x16x32_bf16 v[42:45], v[222:225], v[94:97], v[42:45]
	v_mfma_f32_16x16x32_bf16 v[34:37], v[230:233], v[94:97], v[34:37]
	v_mfma_f32_16x16x32_bf16 v[26:29], v[222:225], v[180:183], v[26:29]
	v_mfma_f32_16x16x32_bf16 v[18:21], v[230:233], v[180:183], v[18:21]
	v_mfma_f32_16x16x32_bf16 v[10:13], v[222:225], v[188:191], v[10:13]
	v_mfma_f32_16x16x32_bf16 v[2:5], v[230:233], v[188:191], v[2:5]
	s_setprio 0
	s_add_i32 s83, s83, 2
	s_add_u32 s81, s81, 0x100
	s_addc_u32 s82, s82, 0
	s_cmp_gt_u32 s83, 13
	s_mov_b64 s[36:37], s[62:63]
	s_barrier
	s_cbranch_scc0 .LBB0_1099
	v_lshl_or_b32 v58, s27, 8, v174
	v_mov_b32_e32 v177, v1
	v_ashrrev_i32_e32 v59, 31, v58
	v_lshlrev_b64 v[58:59], 2, v[58:59]
	v_lshl_add_u64 v[66:67], s[46:47], 0, v[58:59]
	v_lshl_add_u64 v[70:71], s[48:49], 0, v[58:59]
	v_lshlrev_b32_e32 v250, 2, v174
	v_add_u32_e32 v250, 0x20840, v250
	ds_read_b128 v[86:89], v250
	ds_read_b128 v[78:81], v250 offset:1024
	ds_read_b128 v[62:65], v250 offset:16
	ds_read_b128 v[58:61], v250 offset:1040
	ds_read_b128 v[94:97], v250 offset:512
	ds_read_b128 v[90:93], v250 offset:1536
	s_nop 0
	ds_read_b128 v[66:69], v250 offset:528
	s_nop 0
	ds_read_b128 v[70:73], v250 offset:1552
	s_lshl_b32 s3, s3, 8
	v_lshl_or_b32 v176, s27, 7, v174
	v_add_u32_e32 v184, s3, v177
	v_lshl_add_u32 v177, v177, 3, s33
	ds_read_b64 v[178:179], v177
	s_movk_i32 s27, 0xb00
	s_and_b64 vcc, exec, s[60:61]
	s_waitcnt lgkmcnt(0)
	v_xor_b32_e32 v89, 0x80000000, v89
	v_xor_b32_e32 v88, 0x80000000, v88
	v_pk_fma_f32 v[160:161], v[88:89], v[178:179], v[160:161] op_sel_hi:[1,0,1]
	v_pk_fma_f32 v[158:159], v[86:87], v[178:179], v[158:159] op_sel_hi:[1,0,1] neg_lo:[1,0,0] neg_hi:[1,0,0]
	v_pk_fma_f32 v[160:161], v[178:179], v[160:161], v[80:81] op_sel:[1,0,0]
	v_pk_fma_f32 v[158:159], v[178:179], v[158:159], v[78:79] op_sel:[1,0,0]
	v_pk_fma_f32 v[154:155], v[94:95], v[178:179], v[154:155] op_sel_hi:[1,0,1] neg_lo:[1,0,0] neg_hi:[1,0,0]
	v_mul_f32_e32 v182, 0xbfb8aa3b, v160
	v_pk_fma_f32 v[180:181], v[178:179], v[154:155], v[90:91] op_sel:[1,0,0]
	v_mul_f32_e32 v154, 0xbfb8aa3b, v158
	v_mul_f32_e32 v155, 0xbfb8aa3b, v159
	v_mul_f32_e32 v183, 0xbfb8aa3b, v161
	v_exp_f32_e32 v154, v154
	v_exp_f32_e32 v155, v155
	v_exp_f32_e32 v182, v182
	v_exp_f32_e32 v183, v183
	v_add_f32_e32 v154, 1.0, v154
	v_add_f32_e32 v155, 1.0, v155
	v_add_f32_e32 v182, 1.0, v182
	v_add_f32_e32 v183, 1.0, v183
	v_rcp_f32_e32 v154, v154
	v_rcp_f32_e32 v155, v155
	v_rcp_f32_e32 v182, v182
	v_rcp_f32_e32 v183, v183
	v_xor_b32_e32 v97, 0x80000000, v97
	v_xor_b32_e32 v96, 0x80000000, v96
	v_xor_b32_e32 v65, 0x80000000, v65
	v_xor_b32_e32 v64, 0x80000000, v64
	v_pk_fma_f32 v[156:157], v[96:97], v[178:179], v[156:157] op_sel_hi:[1,0,1]
	v_pk_fma_f32 v[152:153], v[64:65], v[178:179], v[152:153] op_sel_hi:[1,0,1]
	v_pk_fma_f32 v[150:151], v[62:63], v[178:179], v[150:151] op_sel_hi:[1,0,1] neg_lo:[1,0,0] neg_hi:[1,0,0]
	v_pk_fma_f32 v[156:157], v[178:179], v[156:157], v[92:93] op_sel:[1,0,0]
	v_pk_mul_f32 v[160:161], v[160:161], v[182:183]
	v_pk_mul_f32 v[158:159], v[158:159], v[154:155]
	v_pk_fma_f32 v[152:153], v[178:179], v[152:153], v[60:61] op_sel:[1,0,0]
	v_pk_fma_f32 v[150:151], v[178:179], v[150:151], v[58:59] op_sel:[1,0,0]
	v_pk_mul_f32 v[154:155], v[156:157], v[160:161]
	v_pk_mul_f32 v[156:157], v[180:181], v[158:159]
	v_mul_f32_e32 v158, 0xbfb8aa3b, v150
	v_mul_f32_e32 v159, 0xbfb8aa3b, v151
	v_mul_f32_e32 v160, 0xbfb8aa3b, v152
	v_mul_f32_e32 v161, 0xbfb8aa3b, v153
	v_exp_f32_e32 v158, v158
	v_exp_f32_e32 v159, v159
	v_exp_f32_e32 v160, v160
	v_exp_f32_e32 v161, v161
	v_add_f32_e32 v158, 1.0, v158
	v_add_f32_e32 v159, 1.0, v159
	v_add_f32_e32 v160, 1.0, v160
	v_add_f32_e32 v161, 1.0, v161
	v_rcp_f32_e32 v158, v158
	v_rcp_f32_e32 v159, v159
	v_rcp_f32_e32 v160, v160
	v_rcp_f32_e32 v161, v161
	v_xor_b32_e32 v69, 0x80000000, v69
	v_xor_b32_e32 v68, 0x80000000, v68
	v_pk_fma_f32 v[148:149], v[68:69], v[178:179], v[148:149] op_sel_hi:[1,0,1]
	v_pk_fma_f32 v[146:147], v[66:67], v[178:179], v[146:147] op_sel_hi:[1,0,1] neg_lo:[1,0,0] neg_hi:[1,0,0]
	v_pk_fma_f32 v[148:149], v[178:179], v[148:149], v[72:73] op_sel:[1,0,0]
	v_pk_fma_f32 v[146:147], v[178:179], v[146:147], v[70:71] op_sel:[1,0,0]
	v_pk_mul_f32 v[152:153], v[152:153], v[160:161]
	v_pk_mul_f32 v[150:151], v[150:151], v[158:159]
	v_mul_lo_u32 v158, v184, s27
	v_pk_mul_f32 v[152:153], v[148:149], v[152:153]
	v_pk_mul_f32 v[148:149], v[146:147], v[150:151]
	v_add_lshl_u32 v150, v158, v176, 1
	v_cvt_pk_bf16_f32 v146, v156, v157
	v_cvt_pk_bf16_f32 v147, v154, v155
	v_cvt_pk_bf16_f32 v148, v148, v149
	v_cvt_pk_bf16_f32 v149, v152, v153
	buffer_store_dwordx4 v[146:149], v150, s[28:31], 0 offen sc1
	ds_read_b64 v[146:147], v177 offset:128
	s_waitcnt lgkmcnt(0)
	v_pk_fma_f32 v[142:143], v[86:87], v[146:147], v[142:143] op_sel_hi:[1,0,1] neg_lo:[1,0,0] neg_hi:[1,0,0]
	s_nop 0
	v_pk_fma_f32 v[142:143], v[146:147], v[142:143], v[78:79] op_sel:[1,0,0]
	v_pk_fma_f32 v[144:145], v[88:89], v[146:147], v[144:145] op_sel_hi:[1,0,1]
	v_mul_f32_e32 v148, 0xbfb8aa3b, v142
	v_mul_f32_e32 v149, 0xbfb8aa3b, v143
	v_pk_fma_f32 v[144:145], v[146:147], v[144:145], v[80:81] op_sel:[1,0,0]
	v_exp_f32_e32 v148, v148
	v_exp_f32_e32 v149, v149
	v_mul_f32_e32 v150, 0xbfb8aa3b, v144
	v_mul_f32_e32 v151, 0xbfb8aa3b, v145
	v_exp_f32_e32 v150, v150
	v_exp_f32_e32 v151, v151
	v_add_f32_e32 v148, 1.0, v148
	v_add_f32_e32 v149, 1.0, v149
	v_rcp_f32_e32 v148, v148
	v_rcp_f32_e32 v149, v149
	v_add_f32_e32 v150, 1.0, v150
	v_add_f32_e32 v151, 1.0, v151
	v_rcp_f32_e32 v150, v150
	v_rcp_f32_e32 v151, v151
	v_pk_fma_f32 v[138:139], v[94:95], v[146:147], v[138:139] op_sel_hi:[1,0,1] neg_lo:[1,0,0] neg_hi:[1,0,0]
	v_pk_fma_f32 v[134:135], v[62:63], v[146:147], v[134:135] op_sel_hi:[1,0,1] neg_lo:[1,0,0] neg_hi:[1,0,0]
	v_pk_fma_f32 v[138:139], v[146:147], v[138:139], v[90:91] op_sel:[1,0,0]
	v_pk_mul_f32 v[142:143], v[142:143], v[148:149]
	v_pk_fma_f32 v[134:135], v[146:147], v[134:135], v[58:59] op_sel:[1,0,0]
	v_pk_fma_f32 v[140:141], v[96:97], v[146:147], v[140:141] op_sel_hi:[1,0,1]
	v_pk_mul_f32 v[138:139], v[138:139], v[142:143]
	v_pk_fma_f32 v[136:137], v[64:65], v[146:147], v[136:137] op_sel_hi:[1,0,1]
	v_mul_f32_e32 v142, 0xbfb8aa3b, v134
	v_mul_f32_e32 v143, 0xbfb8aa3b, v135
	v_pk_fma_f32 v[140:141], v[146:147], v[140:141], v[92:93] op_sel:[1,0,0]
	v_pk_mul_f32 v[144:145], v[144:145], v[150:151]
	v_pk_fma_f32 v[136:137], v[146:147], v[136:137], v[60:61] op_sel:[1,0,0]
	v_exp_f32_e32 v142, v142
	v_exp_f32_e32 v143, v143
	v_pk_mul_f32 v[140:141], v[140:141], v[144:145]
	v_mul_f32_e32 v144, 0xbfb8aa3b, v136
	v_mul_f32_e32 v145, 0xbfb8aa3b, v137
	v_exp_f32_e32 v144, v144
	v_exp_f32_e32 v145, v145
	v_add_f32_e32 v142, 1.0, v142
	v_add_f32_e32 v143, 1.0, v143
	v_rcp_f32_e32 v142, v142
	v_rcp_f32_e32 v143, v143
	v_add_f32_e32 v144, 1.0, v144
	v_add_f32_e32 v145, 1.0, v145
	v_rcp_f32_e32 v144, v144
	v_rcp_f32_e32 v145, v145
	v_pk_fma_f32 v[130:131], v[66:67], v[146:147], v[130:131] op_sel_hi:[1,0,1] neg_lo:[1,0,0] neg_hi:[1,0,0]
	v_pk_mul_f32 v[134:135], v[134:135], v[142:143]
	v_pk_fma_f32 v[130:131], v[146:147], v[130:131], v[70:71] op_sel:[1,0,0]
	v_pk_fma_f32 v[132:133], v[68:69], v[146:147], v[132:133] op_sel_hi:[1,0,1]
	v_pk_mul_f32 v[134:135], v[130:131], v[134:135]
	v_add_u32_e32 v130, 0xb000, v176
	v_pk_fma_f32 v[132:133], v[146:147], v[132:133], v[72:73] op_sel:[1,0,0]
	v_pk_mul_f32 v[136:137], v[136:137], v[144:145]
	v_add_lshl_u32 v131, v158, v130, 1
	v_pk_mul_f32 v[136:137], v[132:133], v[136:137]
	v_cvt_pk_bf16_f32 v132, v138, v139
	v_cvt_pk_bf16_f32 v133, v140, v141
	v_cvt_pk_bf16_f32 v134, v134, v135
	s_nop 0
	v_cvt_pk_bf16_f32 v135, v136, v137
	buffer_store_dwordx4 v[132:135], v131, s[28:31], 0 offen sc1
	v_mov_b32_e32 v131, v171
	s_nop 0
	v_add_u32_e32 v138, s3, v131
	v_lshl_add_u32 v131, v131, 3, s33
	ds_read_b64 v[132:133], v131
	s_waitcnt lgkmcnt(0)
	v_pk_fma_f32 v[128:129], v[88:89], v[132:133], v[128:129] op_sel_hi:[1,0,1]
	v_pk_fma_f32 v[126:127], v[86:87], v[132:133], v[126:127] op_sel_hi:[1,0,1] neg_lo:[1,0,0] neg_hi:[1,0,0]
	v_pk_fma_f32 v[128:129], v[132:133], v[128:129], v[80:81] op_sel:[1,0,0]
	v_pk_fma_f32 v[126:127], v[132:133], v[126:127], v[78:79] op_sel:[1,0,0]
	v_mul_f32_e32 v136, 0xbfb8aa3b, v128
	v_mul_f32_e32 v134, 0xbfb8aa3b, v126
	v_mul_f32_e32 v135, 0xbfb8aa3b, v127
	v_mul_f32_e32 v137, 0xbfb8aa3b, v129
	v_exp_f32_e32 v134, v134
	v_exp_f32_e32 v135, v135
	v_exp_f32_e32 v136, v136
	v_exp_f32_e32 v137, v137
	v_add_f32_e32 v134, 1.0, v134
	v_add_f32_e32 v135, 1.0, v135
	v_add_f32_e32 v136, 1.0, v136
	v_add_f32_e32 v137, 1.0, v137
	v_rcp_f32_e32 v134, v134
	v_rcp_f32_e32 v135, v135
	v_rcp_f32_e32 v136, v136
	v_rcp_f32_e32 v137, v137
	v_pk_fma_f32 v[124:125], v[96:97], v[132:133], v[124:125] op_sel_hi:[1,0,1]
	v_pk_fma_f32 v[122:123], v[94:95], v[132:133], v[122:123] op_sel_hi:[1,0,1] neg_lo:[1,0,0] neg_hi:[1,0,0]
	v_pk_fma_f32 v[120:121], v[64:65], v[132:133], v[120:121] op_sel_hi:[1,0,1]
	v_pk_fma_f32 v[118:119], v[62:63], v[132:133], v[118:119] op_sel_hi:[1,0,1] neg_lo:[1,0,0] neg_hi:[1,0,0]
	v_pk_fma_f32 v[124:125], v[132:133], v[124:125], v[92:93] op_sel:[1,0,0]
	v_pk_fma_f32 v[122:123], v[132:133], v[122:123], v[90:91] op_sel:[1,0,0]
	v_pk_mul_f32 v[128:129], v[128:129], v[136:137]
	v_pk_mul_f32 v[126:127], v[126:127], v[134:135]
	v_pk_fma_f32 v[120:121], v[132:133], v[120:121], v[60:61] op_sel:[1,0,0]
	v_pk_fma_f32 v[118:119], v[132:133], v[118:119], v[58:59] op_sel:[1,0,0]
	v_pk_mul_f32 v[124:125], v[124:125], v[128:129]
	v_pk_mul_f32 v[122:123], v[122:123], v[126:127]
	v_mul_f32_e32 v126, 0xbfb8aa3b, v118
	v_mul_f32_e32 v127, 0xbfb8aa3b, v119
	v_mul_f32_e32 v128, 0xbfb8aa3b, v120
	v_mul_f32_e32 v129, 0xbfb8aa3b, v121
	v_exp_f32_e32 v126, v126
	v_exp_f32_e32 v127, v127
	v_exp_f32_e32 v128, v128
	v_exp_f32_e32 v129, v129
	v_add_f32_e32 v126, 1.0, v126
	v_add_f32_e32 v127, 1.0, v127
	v_add_f32_e32 v128, 1.0, v128
	v_add_f32_e32 v129, 1.0, v129
	v_rcp_f32_e32 v126, v126
	v_rcp_f32_e32 v127, v127
	v_rcp_f32_e32 v128, v128
	v_rcp_f32_e32 v129, v129
	v_pk_fma_f32 v[116:117], v[68:69], v[132:133], v[116:117] op_sel_hi:[1,0,1]
	v_pk_fma_f32 v[114:115], v[66:67], v[132:133], v[114:115] op_sel_hi:[1,0,1] neg_lo:[1,0,0] neg_hi:[1,0,0]
	v_pk_fma_f32 v[116:117], v[132:133], v[116:117], v[72:73] op_sel:[1,0,0]
	v_pk_fma_f32 v[114:115], v[132:133], v[114:115], v[70:71] op_sel:[1,0,0]
	v_pk_mul_f32 v[120:121], v[120:121], v[128:129]
	v_pk_mul_f32 v[118:119], v[118:119], v[126:127]
	v_mul_lo_u32 v126, v138, s27
	v_pk_mul_f32 v[120:121], v[116:117], v[120:121]
	v_pk_mul_f32 v[116:117], v[114:115], v[118:119]
	v_add_lshl_u32 v118, v126, v176, 1
	v_cvt_pk_bf16_f32 v114, v122, v123
	v_cvt_pk_bf16_f32 v115, v124, v125
	v_cvt_pk_bf16_f32 v116, v116, v117
	v_cvt_pk_bf16_f32 v117, v120, v121
	buffer_store_dwordx4 v[114:117], v118, s[28:31], 0 offen sc1
	ds_read_b64 v[114:115], v131 offset:128
	s_waitcnt lgkmcnt(0)
	v_pk_fma_f32 v[112:113], v[88:89], v[114:115], v[112:113] op_sel_hi:[1,0,1]
	v_pk_fma_f32 v[110:111], v[86:87], v[114:115], v[110:111] op_sel_hi:[1,0,1] neg_lo:[1,0,0] neg_hi:[1,0,0]
	v_pk_fma_f32 v[112:113], v[114:115], v[112:113], v[80:81] op_sel:[1,0,0]
	v_pk_fma_f32 v[110:111], v[114:115], v[110:111], v[78:79] op_sel:[1,0,0]
	v_mul_f32_e32 v118, 0xbfb8aa3b, v112
	v_mul_f32_e32 v116, 0xbfb8aa3b, v110
	v_mul_f32_e32 v117, 0xbfb8aa3b, v111
	v_mul_f32_e32 v119, 0xbfb8aa3b, v113
	v_exp_f32_e32 v116, v116
	v_exp_f32_e32 v117, v117
	v_exp_f32_e32 v118, v118
	v_exp_f32_e32 v119, v119
	v_add_f32_e32 v116, 1.0, v116
	v_add_f32_e32 v117, 1.0, v117
	v_add_f32_e32 v118, 1.0, v118
	v_add_f32_e32 v119, 1.0, v119
	v_rcp_f32_e32 v116, v116
	v_rcp_f32_e32 v117, v117
	v_rcp_f32_e32 v118, v118
	v_rcp_f32_e32 v119, v119
	v_pk_fma_f32 v[108:109], v[96:97], v[114:115], v[108:109] op_sel_hi:[1,0,1]
	v_pk_fma_f32 v[106:107], v[94:95], v[114:115], v[106:107] op_sel_hi:[1,0,1] neg_lo:[1,0,0] neg_hi:[1,0,0]
	v_pk_fma_f32 v[104:105], v[64:65], v[114:115], v[104:105] op_sel_hi:[1,0,1]
	v_pk_fma_f32 v[102:103], v[62:63], v[114:115], v[102:103] op_sel_hi:[1,0,1] neg_lo:[1,0,0] neg_hi:[1,0,0]
	v_pk_fma_f32 v[108:109], v[114:115], v[108:109], v[92:93] op_sel:[1,0,0]
	v_pk_fma_f32 v[106:107], v[114:115], v[106:107], v[90:91] op_sel:[1,0,0]
	v_pk_mul_f32 v[112:113], v[112:113], v[118:119]
	v_pk_mul_f32 v[110:111], v[110:111], v[116:117]
	v_pk_fma_f32 v[104:105], v[114:115], v[104:105], v[60:61] op_sel:[1,0,0]
	v_pk_fma_f32 v[102:103], v[114:115], v[102:103], v[58:59] op_sel:[1,0,0]
	v_pk_mul_f32 v[108:109], v[108:109], v[112:113]
	v_pk_mul_f32 v[106:107], v[106:107], v[110:111]
	v_mul_f32_e32 v110, 0xbfb8aa3b, v102
	v_mul_f32_e32 v111, 0xbfb8aa3b, v103
	v_mul_f32_e32 v112, 0xbfb8aa3b, v104
	v_mul_f32_e32 v113, 0xbfb8aa3b, v105
	v_exp_f32_e32 v110, v110
	v_exp_f32_e32 v111, v111
	v_exp_f32_e32 v112, v112
	v_exp_f32_e32 v113, v113
	v_add_f32_e32 v110, 1.0, v110
	v_add_f32_e32 v111, 1.0, v111
	v_add_f32_e32 v112, 1.0, v112
	v_add_f32_e32 v113, 1.0, v113
	v_rcp_f32_e32 v110, v110
	v_rcp_f32_e32 v111, v111
	v_rcp_f32_e32 v112, v112
	v_rcp_f32_e32 v113, v113
	v_pk_fma_f32 v[100:101], v[68:69], v[114:115], v[100:101] op_sel_hi:[1,0,1]
	v_pk_fma_f32 v[98:99], v[66:67], v[114:115], v[98:99] op_sel_hi:[1,0,1] neg_lo:[1,0,0] neg_hi:[1,0,0]
	v_pk_fma_f32 v[100:101], v[114:115], v[100:101], v[72:73] op_sel:[1,0,0]
	v_pk_fma_f32 v[98:99], v[114:115], v[98:99], v[70:71] op_sel:[1,0,0]
	v_pk_mul_f32 v[104:105], v[104:105], v[112:113]
	v_pk_mul_f32 v[102:103], v[102:103], v[110:111]
	v_pk_mul_f32 v[104:105], v[100:101], v[104:105]
	v_pk_mul_f32 v[100:101], v[98:99], v[102:103]
	v_add_lshl_u32 v102, v126, v130, 1
	v_cvt_pk_bf16_f32 v98, v106, v107
	v_cvt_pk_bf16_f32 v99, v108, v109
	v_cvt_pk_bf16_f32 v100, v100, v101
	v_cvt_pk_bf16_f32 v101, v104, v105
	buffer_store_dwordx4 v[98:101], v102, s[28:31], 0 offen sc1
	s_nop 1
	v_mov_b32_e32 v98, v172
	s_nop 0
	v_lshl_add_u32 v105, v98, 3, s33
	v_add_u32_e32 v104, s3, v98
	ds_read_b64 v[98:99], v105
	s_waitcnt lgkmcnt(0)
	v_pk_fma_f32 v[84:85], v[88:89], v[98:99], v[84:85] op_sel_hi:[1,0,1]
	v_pk_fma_f32 v[82:83], v[86:87], v[98:99], v[82:83] op_sel_hi:[1,0,1] neg_lo:[1,0,0] neg_hi:[1,0,0]
	v_pk_fma_f32 v[84:85], v[98:99], v[84:85], v[80:81] op_sel:[1,0,0]
	v_pk_fma_f32 v[82:83], v[98:99], v[82:83], v[78:79] op_sel:[1,0,0]
	v_mul_f32_e32 v102, 0xbfb8aa3b, v84
	v_mul_f32_e32 v100, 0xbfb8aa3b, v82
	v_mul_f32_e32 v101, 0xbfb8aa3b, v83
	v_mul_f32_e32 v103, 0xbfb8aa3b, v85
	v_exp_f32_e32 v100, v100
	v_exp_f32_e32 v101, v101
	v_exp_f32_e32 v102, v102
	v_exp_f32_e32 v103, v103
	v_add_f32_e32 v100, 1.0, v100
	v_add_f32_e32 v101, 1.0, v101
	v_add_f32_e32 v102, 1.0, v102
	v_add_f32_e32 v103, 1.0, v103
	v_rcp_f32_e32 v100, v100
	v_rcp_f32_e32 v101, v101
	v_rcp_f32_e32 v102, v102
	v_rcp_f32_e32 v103, v103
	v_pk_fma_f32 v[76:77], v[96:97], v[98:99], v[76:77] op_sel_hi:[1,0,1]
	v_pk_fma_f32 v[74:75], v[94:95], v[98:99], v[74:75] op_sel_hi:[1,0,1] neg_lo:[1,0,0] neg_hi:[1,0,0]
	v_pk_fma_f32 v[56:57], v[64:65], v[98:99], v[56:57] op_sel_hi:[1,0,1]
	v_pk_fma_f32 v[54:55], v[62:63], v[98:99], v[54:55] op_sel_hi:[1,0,1] neg_lo:[1,0,0] neg_hi:[1,0,0]
	v_pk_fma_f32 v[76:77], v[98:99], v[76:77], v[92:93] op_sel:[1,0,0]
	v_pk_fma_f32 v[74:75], v[98:99], v[74:75], v[90:91] op_sel:[1,0,0]
	v_pk_mul_f32 v[84:85], v[84:85], v[102:103]
	v_pk_mul_f32 v[82:83], v[82:83], v[100:101]
	v_pk_fma_f32 v[56:57], v[98:99], v[56:57], v[60:61] op_sel:[1,0,0]
	v_pk_fma_f32 v[54:55], v[98:99], v[54:55], v[58:59] op_sel:[1,0,0]
	v_pk_mul_f32 v[76:77], v[76:77], v[84:85]
	v_pk_mul_f32 v[74:75], v[74:75], v[82:83]
	v_mul_f32_e32 v82, 0xbfb8aa3b, v54
	v_mul_f32_e32 v83, 0xbfb8aa3b, v55
	v_mul_f32_e32 v84, 0xbfb8aa3b, v56
	v_mul_f32_e32 v85, 0xbfb8aa3b, v57
	v_exp_f32_e32 v82, v82
	v_exp_f32_e32 v83, v83
	v_exp_f32_e32 v84, v84
	v_exp_f32_e32 v85, v85
	v_add_f32_e32 v82, 1.0, v82
	v_add_f32_e32 v83, 1.0, v83
	v_add_f32_e32 v84, 1.0, v84
	v_add_f32_e32 v85, 1.0, v85
	v_rcp_f32_e32 v82, v82
	v_rcp_f32_e32 v83, v83
	v_rcp_f32_e32 v84, v84
	v_rcp_f32_e32 v85, v85
	v_pk_fma_f32 v[52:53], v[68:69], v[98:99], v[52:53] op_sel_hi:[1,0,1]
	v_pk_fma_f32 v[50:51], v[66:67], v[98:99], v[50:51] op_sel_hi:[1,0,1] neg_lo:[1,0,0] neg_hi:[1,0,0]
	v_pk_fma_f32 v[52:53], v[98:99], v[52:53], v[72:73] op_sel:[1,0,0]
	v_pk_fma_f32 v[50:51], v[98:99], v[50:51], v[70:71] op_sel:[1,0,0]
	v_pk_mul_f32 v[56:57], v[56:57], v[84:85]
	v_pk_mul_f32 v[54:55], v[54:55], v[82:83]
	v_mul_lo_u32 v82, v104, s27
	v_pk_mul_f32 v[56:57], v[52:53], v[56:57]
	v_pk_mul_f32 v[52:53], v[50:51], v[54:55]
	v_add_lshl_u32 v54, v82, v176, 1
	v_cvt_pk_bf16_f32 v50, v74, v75
	v_cvt_pk_bf16_f32 v51, v76, v77
	v_cvt_pk_bf16_f32 v52, v52, v53
	v_cvt_pk_bf16_f32 v53, v56, v57
	buffer_store_dwordx4 v[50:53], v54, s[28:31], 0 offen sc1
	ds_read_b64 v[50:51], v105 offset:128
	s_waitcnt lgkmcnt(0)
	v_pk_fma_f32 v[48:49], v[88:89], v[50:51], v[48:49] op_sel_hi:[1,0,1]
	v_pk_fma_f32 v[46:47], v[86:87], v[50:51], v[46:47] op_sel_hi:[1,0,1] neg_lo:[1,0,0] neg_hi:[1,0,0]
	v_pk_fma_f32 v[48:49], v[50:51], v[48:49], v[80:81] op_sel:[1,0,0]
	v_pk_fma_f32 v[46:47], v[50:51], v[46:47], v[78:79] op_sel:[1,0,0]
	v_mul_f32_e32 v54, 0xbfb8aa3b, v48
	v_mul_f32_e32 v52, 0xbfb8aa3b, v46
	v_mul_f32_e32 v53, 0xbfb8aa3b, v47
	v_mul_f32_e32 v55, 0xbfb8aa3b, v49
	v_exp_f32_e32 v52, v52
	v_exp_f32_e32 v53, v53
	v_exp_f32_e32 v54, v54
	v_exp_f32_e32 v55, v55
	v_add_f32_e32 v52, 1.0, v52
	v_add_f32_e32 v53, 1.0, v53
	v_add_f32_e32 v54, 1.0, v54
	v_add_f32_e32 v55, 1.0, v55
	v_rcp_f32_e32 v52, v52
	v_rcp_f32_e32 v53, v53
	v_rcp_f32_e32 v54, v54
	v_rcp_f32_e32 v55, v55
	v_pk_fma_f32 v[44:45], v[96:97], v[50:51], v[44:45] op_sel_hi:[1,0,1]
	v_pk_fma_f32 v[42:43], v[94:95], v[50:51], v[42:43] op_sel_hi:[1,0,1] neg_lo:[1,0,0] neg_hi:[1,0,0]
	v_pk_fma_f32 v[40:41], v[64:65], v[50:51], v[40:41] op_sel_hi:[1,0,1]
	v_pk_fma_f32 v[38:39], v[62:63], v[50:51], v[38:39] op_sel_hi:[1,0,1] neg_lo:[1,0,0] neg_hi:[1,0,0]
	v_pk_fma_f32 v[44:45], v[50:51], v[44:45], v[92:93] op_sel:[1,0,0]
	v_pk_fma_f32 v[42:43], v[50:51], v[42:43], v[90:91] op_sel:[1,0,0]
	v_pk_mul_f32 v[48:49], v[48:49], v[54:55]
	v_pk_mul_f32 v[46:47], v[46:47], v[52:53]
	v_pk_fma_f32 v[40:41], v[50:51], v[40:41], v[60:61] op_sel:[1,0,0]
	v_pk_fma_f32 v[38:39], v[50:51], v[38:39], v[58:59] op_sel:[1,0,0]
	v_pk_mul_f32 v[44:45], v[44:45], v[48:49]
	v_pk_mul_f32 v[42:43], v[42:43], v[46:47]
	v_mul_f32_e32 v46, 0xbfb8aa3b, v38
	v_mul_f32_e32 v47, 0xbfb8aa3b, v39
	v_mul_f32_e32 v48, 0xbfb8aa3b, v40
	v_mul_f32_e32 v49, 0xbfb8aa3b, v41
	v_exp_f32_e32 v46, v46
	v_exp_f32_e32 v47, v47
	v_exp_f32_e32 v48, v48
	v_exp_f32_e32 v49, v49
	v_add_f32_e32 v46, 1.0, v46
	v_add_f32_e32 v47, 1.0, v47
	v_add_f32_e32 v48, 1.0, v48
	v_add_f32_e32 v49, 1.0, v49
	v_rcp_f32_e32 v46, v46
	v_rcp_f32_e32 v47, v47
	v_rcp_f32_e32 v48, v48
	v_rcp_f32_e32 v49, v49
	v_pk_fma_f32 v[36:37], v[68:69], v[50:51], v[36:37] op_sel_hi:[1,0,1]
	v_pk_fma_f32 v[34:35], v[66:67], v[50:51], v[34:35] op_sel_hi:[1,0,1] neg_lo:[1,0,0] neg_hi:[1,0,0]
	v_pk_fma_f32 v[36:37], v[50:51], v[36:37], v[72:73] op_sel:[1,0,0]
	v_pk_fma_f32 v[34:35], v[50:51], v[34:35], v[70:71] op_sel:[1,0,0]
	v_pk_mul_f32 v[40:41], v[40:41], v[48:49]
	v_pk_mul_f32 v[38:39], v[38:39], v[46:47]
	v_pk_mul_f32 v[40:41], v[36:37], v[40:41]
	v_pk_mul_f32 v[36:37], v[34:35], v[38:39]
	v_add_lshl_u32 v38, v82, v130, 1
	v_cvt_pk_bf16_f32 v34, v42, v43
	v_cvt_pk_bf16_f32 v35, v44, v45
	v_cvt_pk_bf16_f32 v36, v36, v37
	v_cvt_pk_bf16_f32 v37, v40, v41
	buffer_store_dwordx4 v[34:37], v38, s[28:31], 0 offen sc1
	s_nop 1
	v_mov_b32_e32 v34, v173
	s_nop 0
	v_lshl_add_u32 v41, v34, 3, s33
	v_add_u32_e32 v40, s3, v34
	ds_read_b64 v[34:35], v41
	s_mov_b32 s3, s77
	s_waitcnt lgkmcnt(0)
	v_pk_fma_f32 v[32:33], v[88:89], v[34:35], v[32:33] op_sel_hi:[1,0,1]
	v_pk_fma_f32 v[30:31], v[86:87], v[34:35], v[30:31] op_sel_hi:[1,0,1] neg_lo:[1,0,0] neg_hi:[1,0,0]
	v_pk_fma_f32 v[32:33], v[34:35], v[32:33], v[80:81] op_sel:[1,0,0]
	v_pk_fma_f32 v[30:31], v[34:35], v[30:31], v[78:79] op_sel:[1,0,0]
	v_mul_f32_e32 v38, 0xbfb8aa3b, v32
	v_mul_f32_e32 v36, 0xbfb8aa3b, v30
	v_mul_f32_e32 v37, 0xbfb8aa3b, v31
	v_mul_f32_e32 v39, 0xbfb8aa3b, v33
	v_exp_f32_e32 v36, v36
	v_exp_f32_e32 v37, v37
	v_exp_f32_e32 v38, v38
	v_exp_f32_e32 v39, v39
	v_add_f32_e32 v36, 1.0, v36
	v_add_f32_e32 v37, 1.0, v37
	v_add_f32_e32 v38, 1.0, v38
	v_add_f32_e32 v39, 1.0, v39
	v_rcp_f32_e32 v36, v36
	v_rcp_f32_e32 v37, v37
	v_rcp_f32_e32 v38, v38
	v_rcp_f32_e32 v39, v39
	v_pk_fma_f32 v[28:29], v[96:97], v[34:35], v[28:29] op_sel_hi:[1,0,1]
	v_pk_fma_f32 v[26:27], v[94:95], v[34:35], v[26:27] op_sel_hi:[1,0,1] neg_lo:[1,0,0] neg_hi:[1,0,0]
	v_pk_fma_f32 v[24:25], v[64:65], v[34:35], v[24:25] op_sel_hi:[1,0,1]
	v_pk_fma_f32 v[22:23], v[62:63], v[34:35], v[22:23] op_sel_hi:[1,0,1] neg_lo:[1,0,0] neg_hi:[1,0,0]
	v_pk_fma_f32 v[28:29], v[34:35], v[28:29], v[92:93] op_sel:[1,0,0]
	v_pk_fma_f32 v[26:27], v[34:35], v[26:27], v[90:91] op_sel:[1,0,0]
	v_pk_mul_f32 v[32:33], v[32:33], v[38:39]
	v_pk_mul_f32 v[30:31], v[30:31], v[36:37]
	v_pk_fma_f32 v[24:25], v[34:35], v[24:25], v[60:61] op_sel:[1,0,0]
	v_pk_fma_f32 v[22:23], v[34:35], v[22:23], v[58:59] op_sel:[1,0,0]
	v_pk_mul_f32 v[28:29], v[28:29], v[32:33]
	v_pk_mul_f32 v[26:27], v[26:27], v[30:31]
	v_mul_f32_e32 v30, 0xbfb8aa3b, v22
	v_mul_f32_e32 v31, 0xbfb8aa3b, v23
	v_mul_f32_e32 v32, 0xbfb8aa3b, v24
	v_mul_f32_e32 v33, 0xbfb8aa3b, v25
	v_exp_f32_e32 v30, v30
	v_exp_f32_e32 v31, v31
	v_exp_f32_e32 v32, v32
	v_exp_f32_e32 v33, v33
	v_add_f32_e32 v30, 1.0, v30
	v_add_f32_e32 v31, 1.0, v31
	v_add_f32_e32 v32, 1.0, v32
	v_add_f32_e32 v33, 1.0, v33
	v_rcp_f32_e32 v30, v30
	v_rcp_f32_e32 v31, v31
	v_rcp_f32_e32 v32, v32
	v_rcp_f32_e32 v33, v33
	v_pk_fma_f32 v[20:21], v[68:69], v[34:35], v[20:21] op_sel_hi:[1,0,1]
	v_pk_fma_f32 v[18:19], v[66:67], v[34:35], v[18:19] op_sel_hi:[1,0,1] neg_lo:[1,0,0] neg_hi:[1,0,0]
	v_pk_fma_f32 v[20:21], v[34:35], v[20:21], v[72:73] op_sel:[1,0,0]
	v_pk_fma_f32 v[18:19], v[34:35], v[18:19], v[70:71] op_sel:[1,0,0]
	v_pk_mul_f32 v[24:25], v[24:25], v[32:33]
	v_pk_mul_f32 v[22:23], v[22:23], v[30:31]
	v_mul_lo_u32 v30, v40, s27
	v_pk_mul_f32 v[24:25], v[20:21], v[24:25]
	v_pk_mul_f32 v[20:21], v[18:19], v[22:23]
	v_add_lshl_u32 v22, v30, v176, 1
	v_cvt_pk_bf16_f32 v18, v26, v27
	v_cvt_pk_bf16_f32 v19, v28, v29
	v_cvt_pk_bf16_f32 v20, v20, v21
	v_cvt_pk_bf16_f32 v21, v24, v25
	buffer_store_dwordx4 v[18:21], v22, s[28:31], 0 offen sc1
	ds_read_b64 v[18:19], v41 offset:128
	s_mov_b32 s27, s58
	s_waitcnt lgkmcnt(0)
	v_pk_fma_f32 v[16:17], v[88:89], v[18:19], v[16:17] op_sel_hi:[1,0,1]
	v_pk_fma_f32 v[14:15], v[86:87], v[18:19], v[14:15] op_sel_hi:[1,0,1] neg_lo:[1,0,0] neg_hi:[1,0,0]
	v_pk_fma_f32 v[16:17], v[18:19], v[16:17], v[80:81] op_sel:[1,0,0]
	v_pk_fma_f32 v[14:15], v[18:19], v[14:15], v[78:79] op_sel:[1,0,0]
	v_mul_f32_e32 v22, 0xbfb8aa3b, v16
	v_mul_f32_e32 v20, 0xbfb8aa3b, v14
	v_mul_f32_e32 v21, 0xbfb8aa3b, v15
	v_mul_f32_e32 v23, 0xbfb8aa3b, v17
	v_exp_f32_e32 v20, v20
	v_exp_f32_e32 v21, v21
	v_exp_f32_e32 v22, v22
	v_exp_f32_e32 v23, v23
	v_add_f32_e32 v20, 1.0, v20
	v_add_f32_e32 v21, 1.0, v21
	v_add_f32_e32 v22, 1.0, v22
	v_add_f32_e32 v23, 1.0, v23
	v_rcp_f32_e32 v20, v20
	v_rcp_f32_e32 v21, v21
	v_rcp_f32_e32 v22, v22
	v_rcp_f32_e32 v23, v23
	v_pk_fma_f32 v[12:13], v[96:97], v[18:19], v[12:13] op_sel_hi:[1,0,1]
	v_pk_fma_f32 v[10:11], v[94:95], v[18:19], v[10:11] op_sel_hi:[1,0,1] neg_lo:[1,0,0] neg_hi:[1,0,0]
	v_pk_fma_f32 v[8:9], v[64:65], v[18:19], v[8:9] op_sel_hi:[1,0,1]
	v_pk_fma_f32 v[6:7], v[62:63], v[18:19], v[6:7] op_sel_hi:[1,0,1] neg_lo:[1,0,0] neg_hi:[1,0,0]
	v_pk_fma_f32 v[12:13], v[18:19], v[12:13], v[92:93] op_sel:[1,0,0]
	v_pk_fma_f32 v[10:11], v[18:19], v[10:11], v[90:91] op_sel:[1,0,0]
	v_pk_mul_f32 v[16:17], v[16:17], v[22:23]
	v_pk_mul_f32 v[14:15], v[14:15], v[20:21]
	v_pk_fma_f32 v[8:9], v[18:19], v[8:9], v[60:61] op_sel:[1,0,0]
	v_pk_fma_f32 v[6:7], v[18:19], v[6:7], v[58:59] op_sel:[1,0,0]
	v_pk_mul_f32 v[12:13], v[12:13], v[16:17]
	v_pk_mul_f32 v[10:11], v[10:11], v[14:15]
	v_mul_f32_e32 v14, 0xbfb8aa3b, v6
	v_mul_f32_e32 v15, 0xbfb8aa3b, v7
	v_mul_f32_e32 v16, 0xbfb8aa3b, v8
	v_mul_f32_e32 v17, 0xbfb8aa3b, v9
	v_exp_f32_e32 v14, v14
	v_exp_f32_e32 v15, v15
	v_exp_f32_e32 v16, v16
	v_exp_f32_e32 v17, v17
	v_add_f32_e32 v14, 1.0, v14
	v_add_f32_e32 v15, 1.0, v15
	v_add_f32_e32 v16, 1.0, v16
	v_add_f32_e32 v17, 1.0, v17
	v_rcp_f32_e32 v14, v14
	v_rcp_f32_e32 v15, v15
	v_rcp_f32_e32 v16, v16
	v_rcp_f32_e32 v17, v17
	v_pk_fma_f32 v[4:5], v[68:69], v[18:19], v[4:5] op_sel_hi:[1,0,1]
	v_pk_fma_f32 v[2:3], v[66:67], v[18:19], v[2:3] op_sel_hi:[1,0,1] neg_lo:[1,0,0] neg_hi:[1,0,0]
	v_pk_fma_f32 v[4:5], v[18:19], v[4:5], v[72:73] op_sel:[1,0,0]
	v_pk_fma_f32 v[2:3], v[18:19], v[2:3], v[70:71] op_sel:[1,0,0]
	v_pk_mul_f32 v[8:9], v[8:9], v[16:17]
	v_pk_mul_f32 v[6:7], v[6:7], v[14:15]
	v_pk_mul_f32 v[8:9], v[4:5], v[8:9]
	v_pk_mul_f32 v[4:5], v[2:3], v[6:7]
	v_add_lshl_u32 v6, v30, v130, 1
	v_cvt_pk_bf16_f32 v2, v10, v11
	v_cvt_pk_bf16_f32 v3, v12, v13
	v_cvt_pk_bf16_f32 v4, v4, v5
	v_cvt_pk_bf16_f32 v5, v8, v9
	buffer_store_dwordx4 v[2:5], v6, s[28:31], 0 offen sc1
	s_cbranch_vccz .LBB0_1098
	s_waitcnt vmcnt(0)
	v_readlane_b32 s76, v255, 13
	s_cmpk_gt_u32 s38, 0xff
	v_readlane_b32 s77, v255, 14
	s_cbranch_scc1 .LBB0_1103
	s_barrier

	.amdhsa_kernel _Z19hgrn2_chunkmlp_mega6Params
		.amdhsa_group_segment_fixed_size 2048
		.amdhsa_private_segment_fixed_size 0
		.amdhsa_kernarg_size 424
		.amdhsa_user_sgpr_count 2
		.amdhsa_user_sgpr_dispatch_ptr 0
		.amdhsa_user_sgpr_queue_ptr 0
		.amdhsa_user_sgpr_kernarg_segment_ptr 1
		.amdhsa_user_sgpr_dispatch_id 0
		.amdhsa_user_sgpr_kernarg_preload_length 0
		.amdhsa_user_sgpr_kernarg_preload_offset 0
		.amdhsa_user_sgpr_private_segment_size 0
		.amdhsa_uses_dynamic_stack 0
		.amdhsa_enable_private_segment 0
		.amdhsa_system_sgpr_workgroup_id_x 1
		.amdhsa_system_sgpr_workgroup_id_y 0
		.amdhsa_system_sgpr_workgroup_id_z 0
		.amdhsa_system_sgpr_workgroup_info 0
		.amdhsa_system_vgpr_workitem_id 2
		.amdhsa_next_free_vgpr 256
		.amdhsa_next_free_sgpr 102
		.amdhsa_accum_offset 256
		.amdhsa_reserve_vcc 1
		.amdhsa_float_round_mode_32 0
		.amdhsa_float_round_mode_16_64 0
		.amdhsa_float_denorm_mode_32 3
		.amdhsa_float_denorm_mode_16_64 3
		.amdhsa_dx10_clamp 1
		.amdhsa_ieee_mode 1
		.amdhsa_fp16_overflow 0
		.amdhsa_tg_split 0
		.amdhsa_exception_fp_ieee_invalid_op 0
		.amdhsa_exception_fp_denorm_src 0
		.amdhsa_exception_fp_ieee_div_zero 0
		.amdhsa_exception_fp_ieee_overflow 0
		.amdhsa_exception_fp_ieee_underflow 0
		.amdhsa_exception_fp_ieee_inexact 0
		.amdhsa_exception_int_div_zero 0
	.end_amdhsa_kernel

amdhsa.kernels:
  - .agpr_count:     0
    .args:
      - .offset:         0
        .size:           168
        .value_kind:     by_value
      - .offset:         168
        .size:           4
        .value_kind:     hidden_block_count_x
      - .offset:         172
        .size:           4
        .value_kind:     hidden_block_count_y
      - .offset:         176
        .size:           4
        .value_kind:     hidden_block_count_z
      - .offset:         180
        .size:           2
        .value_kind:     hidden_group_size_x
      - .offset:         182
        .size:           2
        .value_kind:     hidden_group_size_y
      - .offset:         184
        .size:           2
        .value_kind:     hidden_group_size_z
      - .offset:         186
        .size:           2
        .value_kind:     hidden_remainder_x
      - .offset:         188
        .size:           2
        .value_kind:     hidden_remainder_y
      - .offset:         190
        .size:           2
        .value_kind:     hidden_remainder_z
      - .offset:         208
        .size:           8
        .value_kind:     hidden_global_offset_x
      - .offset:         216
        .size:           8
        .value_kind:     hidden_global_offset_y
      - .offset:         224
        .size:           8
        .value_kind:     hidden_global_offset_z
      - .offset:         232
        .size:           2
        .value_kind:     hidden_grid_dims
      - .offset:         256
        .size:           8
        .value_kind:     hidden_multigrid_sync_arg
      - .offset:         288
        .size:           4
        .value_kind:     hidden_dynamic_lds_size
    .group_segment_fixed_size: 2048
    .kernarg_segment_align: 8
    .kernarg_segment_size: 424
    .language:       OpenCL C
    .language_version:
      - 2
      - 0
    .max_flat_workgroup_size: 512
    .name:           _Z19hgrn2_chunkmlp_mega6Params
    .private_segment_fixed_size: 0
    .sgpr_count:     108
    .sgpr_spill_count: 245
    .symbol:         _Z19hgrn2_chunkmlp_mega6Params.kd
    .uniform_work_group_size: 1
    .uses_dynamic_stack: false
    .vgpr_count:     256
    .vgpr_spill_count: 0
    .wavefront_size: 64
